# C_align0 + P4: one workgroup barrier per PAIR of key tiles (two 32K pair buffers, both next tiles staged at the pair start, 4-5 tiles of load lead)
# speedup vs baseline: 1.0054x; 1.0040x over previous
; __device__ __forceinline__ void attn_unit(const Params& p, LAS unsigned char* lds, int b, int h, int qb, int tid, int wid, int lane, u64& tacc, v4u& kA, v4u& vA, v4u& kB, v4u& vB, const bool first) {
;     const bf16* proj = (const bf16*)(p.ws + WS_PROJ); const u64* bm = (const u64*)((const unsigned char*)p.out + DO_BM); bf16* attn = (bf16*)(p.ws + WS_CA) + 512;
;     const int r32 = lane & 31, hi = lane >> 5;
;     const size_t rowbase = (size_t)b * SEQ; const int q0 = qb * 256;
;     LAS bf16* stg = (LAS bf16*)(lds + 32768) + wid * 2304;
;     const bf16* Qw = proj + (rowbase + q0 + wid * 32) * NPROJ + PC_Q + h * 64;
;     bf16x8 qr[4];
; #pragma unroll
;     for (int d0 = 0; d0 < 4; ++d0) qr[d0] = *(const bf16x8*)(Qw + (size_t)r32 * NPROJ + d0 * 16 + hi * 8);
;     const int NT = 4 * (qb + 1); const int tcw = 4 * qb + (wid >> 1);
;     const bf16* ksrc = (const bf16*)((const unsigned char*)p.out + DO_KBLK) + (size_t)(b * 8 + h) * 64 * 4096 + wid * 512 + lane * 8;
;     const bf16* vsrc = (const bf16*)((const unsigned char*)p.out + DO_VBLK) + (size_t)(b * 8 + h) * 64 * 4096 + wid * 512 + lane * 8;
;     const u64* bmq = bm + (rowbase + q0 + wid * 32 + r32) * 64;
;     const unsigned stoff = wid * 1024 + lane * 16;
;     const unsigned vboff = 8192 + ((lane >> 4) & 1) * 32 + (lane & 3) * 8 + (4 * hi + ((lane & 15) >> 2)) * 64;
;     float m = 0.f; bool started = false; f32x16 o0, o1, o2;
; #pragma unroll
;     for (int i = 0; i < 16; ++i) { o0[i] = 0.f; o1[i] = 0.f; o2[i] = 0.f; }
;     float negv = -1e30f; asm volatile("" : "+v"(negv));
;     const bf16x8 ones8 = (bf16x8){0x3f80, 0x3f80, 0x3f80, 0x3f80, 0x3f80, 0x3f80, 0x3f80, 0x3f80};
;     v4u mwc = *(const v4u*)bmq, mwn = mwc;
;     if (first) {
;         kB = *(const v4u*)ksrc; vB = *(const v4u*)vsrc;
;         kA = *(const v4u*)(ksrc + (size_t)4096); vA = *(const v4u*)(vsrc + (size_t)4096);
;         *(LAS v4u*)(lds + stoff) = kB; *(LAS v4u*)(lds + 8192 + stoff) = vB;
;         kB = *(const v4u*)(ksrc + (size_t)2 * 4096); vB = *(const v4u*)(vsrc + (size_t)2 * 4096);
;     }
;     bf16x8 Eop[2];
; #pragma unroll
;     for (int s = 0; s < 2; ++s) { v4u e; unsigned* ep = (unsigned*)&e;
; #pragma unroll
;         for (int i = 0; i < 4; ++i) { const int k0 = 4 * s + i + 8 * hi; ep[i] = (r32 == k0 ? 0x3F80u : 0u) | (r32 == k0 + 16 ? 0x3F800000u : 0u); }
;         Eop[s] = __builtin_bit_cast(bf16x8, e); }
.LBB0_3751:
	s_or_b64 exec, exec, s[0:1]
	v_readlane_b32 s0, v243, 56
	v_readlane_b32 s1, v243, 57
	s_andn2_b64 vcc, exec, s[0:1]
	s_waitcnt lgkmcnt(0)
	s_barrier
	s_cbranch_vccnz .LBB0_3772
	v_and_b32_e32 v1, 63, v167
	v_lshlrev_b32_e32 v3, 3, v167
	v_bfe_u32 v2, v167, 5, 1
	v_lshlrev_b32_e32 v158, 4, v1
	v_lshlrev_b32_e32 v1, 1, v167
	v_and_b32_e32 v3, 24, v3
	v_and_b32_e32 v156, 31, v167
	v_lshlrev_b32_e32 v160, 3, v2
	v_and_or_b32 v1, v1, 32, v3
	v_lshlrev_b32_e32 v3, 8, v2
	s_waitcnt vmcnt(2)
	v_and_b32_e32 v4, 0xc0, v158
	v_or3_b32 v157, v3, v4, v1
	v_or_b32_e32 v157, 0x8000, v157
	v_mov_b32_e32 v3, 0x3f80
	v_cmp_eq_u32_e32 vcc, v156, v160
	v_or_b32_e32 v5, 16, v160
	s_lshl_b32 s24, s84, 5
	v_cndmask_b32_e32 v4, 0, v3, vcc
	v_cmp_eq_u32_e32 vcc, v156, v5
	s_lshr_b32 s25, s86, 7
	s_lshl_b32 s2, s84, 10
	v_cndmask_b32_e64 v5, 0, 1.0, vcc
	v_or_b32_e32 v112, v5, v4
	v_or_b32_e32 v4, 1, v160
	v_cmp_eq_u32_e32 vcc, v156, v4
	v_or_b32_e32 v5, 17, v160
	v_readlane_b32 s0, v243, 52
	v_cndmask_b32_e32 v4, 0, v3, vcc
	v_cmp_eq_u32_e32 vcc, v156, v5
	v_readlane_b32 s1, v243, 53
	s_add_u32 s0, s0, s2
	v_cndmask_b32_e64 v5, 0, 1.0, vcc
	v_or_b32_e32 v113, v5, v4
	v_or_b32_e32 v4, 2, v160
	v_cmp_eq_u32_e32 vcc, v156, v4
	v_or_b32_e32 v5, 18, v160
	v_mov_b32_e32 v159, 0
	v_cndmask_b32_e32 v4, 0, v3, vcc
	v_cmp_eq_u32_e32 vcc, v156, v5
	s_addc_u32 s1, s1, 0
	v_readlane_b32 s4, v243, 50
	v_cndmask_b32_e64 v5, 0, 1.0, vcc
	v_or_b32_e32 v114, v5, v4
	v_or_b32_e32 v4, 3, v160
	v_cmp_eq_u32_e32 vcc, v156, v4
	v_or_b32_e32 v5, 19, v160
	v_readlane_b32 s5, v243, 51
	v_cndmask_b32_e32 v4, 0, v3, vcc
	v_cmp_eq_u32_e32 vcc, v156, v5
	s_add_u32 s4, s4, s2
	v_lshl_add_u64 v[164:165], s[0:1], 0, v[158:159]
	v_cndmask_b32_e64 v5, 0, 1.0, vcc
	v_or_b32_e32 v115, v5, v4
	v_or_b32_e32 v4, 4, v160
	v_cmp_eq_u32_e32 vcc, v156, v4
	v_or_b32_e32 v5, 20, v160
	s_mul_i32 s0, s84, 0x1200
	v_cndmask_b32_e32 v4, 0, v3, vcc
	v_cmp_eq_u32_e32 vcc, v156, v5
	s_addc_u32 s5, s5, 0
	s_add_i32 s0, s0, 0
	v_cndmask_b32_e64 v5, 0, 1.0, vcc
	v_or_b32_e32 v116, v5, v4
	v_or_b32_e32 v4, 5, v160
	v_cmp_eq_u32_e32 vcc, v156, v4
	v_or_b32_e32 v5, 21, v160
	s_movk_i32 s1, 0x90
	v_cndmask_b32_e32 v4, 0, v3, vcc
	v_cmp_eq_u32_e32 vcc, v156, v5
	v_lshl_add_u64 v[162:163], s[4:5], 0, v[158:159]
	v_or_b32_e32 v1, s2, v158
	v_cndmask_b32_e64 v5, 0, 1.0, vcc
	v_or_b32_e32 v117, v5, v4
	v_or_b32_e32 v4, 6, v160
	v_cmp_eq_u32_e32 vcc, v156, v4
	v_or_b32_e32 v5, 22, v160
	v_mov_b32_e32 v122, v159
	v_cndmask_b32_e32 v4, 0, v3, vcc
	v_cmp_eq_u32_e32 vcc, v156, v5
	v_mov_b32_e32 v123, v159
	v_mul_u32_u24_e32 v0, 0x1500, v156
	v_cndmask_b32_e64 v5, 0, 1.0, vcc
	v_or_b32_e32 v118, v5, v4
	v_or_b32_e32 v4, 7, v160
	v_cmp_eq_u32_e32 vcc, v156, v4
	v_or_b32_e32 v4, 23, v160
	v_lshl_add_u32 v5, v2, 10, 0
	v_mov_b32_e32 v2, s0
	v_cndmask_b32_e32 v3, 0, v3, vcc
	v_cmp_eq_u32_e32 vcc, v156, v4
	s_waitcnt vmcnt(1)
	v_mad_u32_u24 v9, v156, s1, v2
	v_lshlrev_b32_e32 v2, 4, v167
	v_cndmask_b32_e64 v4, 0, 1.0, vcc
	v_and_b32_e32 v158, 0x70, v2
	v_or_b32_e32 v119, v4, v3
	v_bfe_u32 v4, v167, 3, 3
	v_add_u32_e32 v10, s0, v158
	v_lshl_add_u64 v[2:3], s[82:83], 0, v[158:159]
	s_mov_b64 s[0:1], 0x1b000400
	v_lshl_add_u64 v[166:167], v[2:3], 0, s[0:1]
	v_lshlrev_b32_e32 v2, 10, v4
	v_lshlrev_b32_e32 v7, 4, v156
	v_mul_u32_u24_e32 v3, 0x90, v4
	v_or_b32_e32 v4, 0x2000, v2
	v_or_b32_e32 v6, 0x4000, v2
	v_or_b32_e32 v8, 0x6000, v2
	s_add_u32 s6, s80, 16
	v_mov_b32_e32 v120, v159
	v_mov_b32_e32 v121, v159
	v_mov_b64_e32 v[134:135], v[122:123]
	v_mov_b64_e32 v[126:127], v[122:123]
	v_mov_b64_e32 v[130:131], v[122:123]
	s_mov_b32 s3, 0
	s_addc_u32 s7, s81, 0
	v_or_b32_e32 v168, s24, v156
	v_mov_b32_e32 v169, v159
	s_mov_b64 s[12:13], 0x2000
	s_mov_b64 s[14:15], 0x4000
	v_lshlrev_b32_e32 v158, 1, v0
	v_lshlrev_b32_e32 v170, 1, v160
	s_mov_b64 s[16:17], 0x2000800
	s_brev_b32 s26, 64
	s_mov_b32 s27, 0x10001
	s_mov_b32 s28, 0x20002
	s_mov_b32 s29, 0x40004
	s_mov_b32 s30, 0x80008
	s_mov_b32 s31, 0x100010
	s_mov_b32 s33, 0x200020
	s_mov_b32 s34, 0x400040
	s_mov_b32 s35, 0x800080
	s_mov_b32 s36, 0xefa18f08
	s_mov_b32 s37, 0x41000000
	s_mov_b32 s8, 0x3f803f80
	v_add_u32_e32 v161, v9, v160
	v_add_u32_e32 v198, v10, v3
	v_add_u32_e32 v198, 0x8000, v198
	v_lshlrev_b32_e32 v172, 1, v2
	v_lshlrev_b32_e32 v174, 1, v4
	v_lshlrev_b32_e32 v176, 1, v6
	v_lshlrev_b32_e32 v178, 1, v8
	v_add_u32_e32 v199, 0, v1
	v_bfrev_b32_e32 v0, 1
	v_add_u32_e32 v200, v5, v7
	v_or_b32_e32 v200, 0x8000, v200
	v_mov_b64_e32 v[132:133], v[120:121]
	v_mov_b64_e32 v[124:125], v[120:121]
	v_mov_b64_e32 v[128:129], v[120:121]
	s_branch .LBB0_3754

; __device__ __forceinline__ void attn_unit(const Params& p, LAS unsigned char* lds, int b, int h, int qb, int tid, int wid, int lane, u64& tacc, v4u& kA, v4u& vA, v4u& kB, v4u& vB, const bool first) {
;     ...
;     const bf16* Qw = proj + (rowbase + q0 + wid * 32) * NPROJ + PC_Q + h * 64;
;     bf16x8 qr[4];
; #pragma unroll
;     for (int d0 = 0; d0 < 4; ++d0) qr[d0] = *(const bf16x8*)(Qw + (size_t)r32 * NPROJ + d0 * 16 + hi * 8);
;     const int NT = 4 * (qb + 1); const int tcw = 4 * qb + (wid >> 1);
;     const bf16* ksrc = (const bf16*)((const unsigned char*)p.out + DO_KBLK) + (size_t)(b * 8 + h) * 64 * 4096 + wid * 512 + lane * 8;
;     const bf16* vsrc = (const bf16*)((const unsigned char*)p.out + DO_VBLK) + (size_t)(b * 8 + h) * 64 * 4096 + wid * 512 + lane * 8;
;     const u64* bmq = bm + (rowbase + q0 + wid * 32 + r32) * 64;
;     const unsigned stoff = wid * 1024 + lane * 16;
;     const unsigned vboff = 8192 + ((lane >> 4) & 1) * 32 + (lane & 3) * 8 + (4 * hi + ((lane & 15) >> 2)) * 64;
;     float m = 0.f; bool started = false; f32x16 o0, o1, o2;
; #pragma unroll
;     for (int i = 0; i < 16; ++i) { o0[i] = 0.f; o1[i] = 0.f; o2[i] = 0.f; }
;     float negv = -1e30f; asm volatile("" : "+v"(negv));
;     const bf16x8 ones8 = (bf16x8){0x3f80, 0x3f80, 0x3f80, 0x3f80, 0x3f80, 0x3f80, 0x3f80, 0x3f80};
;     v4u mwc = *(const v4u*)bmq, mwn = mwc;
;     if (first) {
;         kB = *(const v4u*)ksrc; vB = *(const v4u*)vsrc;
;         kA = *(const v4u*)(ksrc + (size_t)4096); vA = *(const v4u*)(vsrc + (size_t)4096);
;     ...
;     const float rl = __builtin_amdgcn_rcpf(o2[0]);
;     LAS unsigned char* stg8 = (LAS unsigned char*)stg;
; #pragma unroll
;     for (int g = 0; g < 4; ++g) {
;         v2u w0, w1; w0.x = cvtpk(o0[4 * g] * rl, o0[4 * g + 1] * rl); w0.y = cvtpk(o0[4 * g + 2] * rl, o0[4 * g + 3] * rl);
;         w1.x = cvtpk(o1[4 * g] * rl, o1[4 * g + 1] * rl); w1.y = cvtpk(o1[4 * g + 2] * rl, o1[4 * g + 3] * rl);
;         *(LAS v2u*)(stg8 + r32 * 144 + (8 * g + 4 * hi) * 2) = w0; *(LAS v2u*)(stg8 + r32 * 144 + (32 + 8 * g + 4 * hi) * 2) = w1;
;     }
;     bf16* Ow = attn + (rowbase + q0 + wid * 32) * CA_PITCH + h * 64;
; #pragma unroll
;     for (int i = 0; i < 4; ++i) { const int row = i * 8 + (lane >> 3), ch = lane & 7; const v4u v = *(const LAS v4u*)(stg8 + row * 144 + ch * 16); *(v4u*)(Ow + (size_t)row * CA_PITCH + ch * 8) = v; }
.LBB0_3755:
	s_nop 8
	v_rcp_f32_e32 v1, v48
	s_lshl_b64 s[0:1], s[18:19], 11
	v_lshl_add_u64 v[10:11], v[192:193], 0, s[0:1]
	v_mov_b32_e32 v173, v159
	s_waitcnt vmcnt(4)
	v_mul_f32_e32 v2, v1, v16
	v_mul_f32_e32 v3, v1, v17
	v_mul_f32_e32 v4, v1, v18
	v_mul_f32_e32 v5, v1, v19
	v_cvt_pk_bf16_f32 v2, v2, v3
	v_cvt_pk_bf16_f32 v3, v4, v5
	v_mul_f32_e32 v4, v1, v32
	v_mul_f32_e32 v5, v1, v33
	v_cvt_pk_bf16_f32 v4, v4, v5
	v_mul_f32_e32 v5, v1, v34
	v_mul_f32_e32 v6, v1, v35
	v_cvt_pk_bf16_f32 v5, v5, v6
	v_add_u32_e32 v6, 0x10000, v161
	ds_write2_b64 v6, v[2:3], v[4:5] offset1:8
	v_mul_f32_e32 v2, v1, v20
	v_mul_f32_e32 v3, v1, v21
	v_cvt_pk_bf16_f32 v2, v2, v3
	v_mul_f32_e32 v3, v1, v22
	v_mul_f32_e32 v4, v1, v23
	v_cvt_pk_bf16_f32 v3, v3, v4
	v_mul_f32_e32 v4, v1, v36
	v_mul_f32_e32 v5, v1, v37
	v_cvt_pk_bf16_f32 v4, v4, v5
	v_mul_f32_e32 v5, v1, v38
	v_mul_f32_e32 v7, v1, v39
	v_cvt_pk_bf16_f32 v5, v5, v7
	ds_write2_b64 v6, v[2:3], v[4:5] offset0:2 offset1:10
	v_mul_f32_e32 v2, v1, v24
	v_mul_f32_e32 v3, v1, v25
	v_cvt_pk_bf16_f32 v2, v2, v3
	v_mul_f32_e32 v3, v1, v26
	v_mul_f32_e32 v4, v1, v27
	v_cvt_pk_bf16_f32 v3, v3, v4
	v_mul_f32_e32 v4, v1, v40
	v_mul_f32_e32 v5, v1, v41
	v_cvt_pk_bf16_f32 v4, v4, v5
	v_mul_f32_e32 v5, v1, v42
	v_mul_f32_e32 v7, v1, v43
	v_cvt_pk_bf16_f32 v5, v5, v7
	ds_write2_b64 v6, v[2:3], v[4:5] offset0:4 offset1:12
	v_mul_f32_e32 v2, v1, v28
	v_mul_f32_e32 v3, v1, v29
	v_cvt_pk_bf16_f32 v2, v2, v3
	v_mul_f32_e32 v3, v1, v30
	v_mul_f32_e32 v4, v1, v31
	v_cvt_pk_bf16_f32 v3, v3, v4
	v_mul_f32_e32 v4, v1, v44
	v_mul_f32_e32 v5, v1, v45
	v_cvt_pk_bf16_f32 v4, v4, v5
	v_mul_f32_e32 v5, v1, v46
	v_mul_f32_e32 v1, v1, v47
	v_cvt_pk_bf16_f32 v5, v5, v1
	ds_write2_b64 v6, v[2:3], v[4:5] offset0:6 offset1:14
	ds_read_b128 v[2:5], v198 offset:32768
	ds_read_b128 v[6:9], v198 offset:33920
	v_lshl_add_u64 v[12:13], v[10:11], 0, v[172:173]
	v_mov_b32_e32 v175, v159
	v_mov_b32_e32 v177, v159
	s_waitcnt lgkmcnt(1)
	global_store_dwordx4 v[12:13], v[2:5], off
	v_lshl_add_u64 v[12:13], v[10:11], 0, v[174:175]
	ds_read_b128 v[2:5], v198 offset:35072
	s_waitcnt lgkmcnt(1)
	global_store_dwordx4 v[12:13], v[6:9], off
	ds_read_b128 v[6:9], v198 offset:36224
	v_lshl_add_u64 v[12:13], v[10:11], 0, v[176:177]
	v_mov_b32_e32 v179, v159
	s_add_i32 s45, s45, 1
	s_waitcnt lgkmcnt(1)
	global_store_dwordx4 v[12:13], v[2:5], off
	s_cmp_eq_u32 s45, 4
	s_nop 0
	v_lshl_add_u64 v[2:3], v[10:11], 0, v[178:179]
	s_waitcnt lgkmcnt(0)
	global_store_dwordx4 v[2:3], v[6:9], off
	s_cbranch_scc1 .LBB0_3753
.LBB0_3756:
	s_cmp_eq_u32 s45, 2
	s_cselect_b32 s0, s41, s42
	s_cmp_eq_u32 s45, 1
	s_cselect_b32 s0, s43, s0
	s_cmp_eq_u32 s45, 0
	s_cselect_b32 s0, s38, s0
	s_lshl_b32 s2, s0, 8
	s_add_u32 s18, s39, s2
	s_addc_u32 s19, s40, 0
	s_mul_i32 s1, s19, 0x2a00
	s_mul_hi_u32 s4, s18, 0x2a00
	s_add_i32 s4, s4, s1
	s_mul_i32 s1, s18, 0x2a00
	s_add_u32 s1, s82, s1
	s_addc_u32 s5, s83, s4
	s_add_u32 s4, s1, s44
	s_addc_u32 s5, s5, 0
	v_lshl_add_u64 v[2:3], s[4:5], 0, v[158:159]
	v_mov_b32_e32 v171, v159
	v_lshl_add_u64 v[2:3], v[2:3], 0, v[170:171]
	v_lshl_add_u64 v[4:5], v[2:3], 0, s[16:17]
	v_add_co_u32_e32 v2, vcc, s26, v2
	v_mov_b32_e32 v1, 0xf149f2ca
	s_nop 0
	v_addc_co_u32_e32 v3, vcc, 0, v3, vcc
	global_load_dwordx4 v[136:139], v[4:5], off offset:32
	global_load_dwordx4 v[140:143], v[4:5], off offset:64
	global_load_dwordx4 v[144:147], v[2:3], off offset:2048
	global_load_dwordx4 v[148:151], v[4:5], off offset:96
	v_mov_b32_e32 v3, s19
	v_or_b32_e32 v2, s18, v156
	v_lshlrev_b64 v[2:3], 9, v[2:3]
	v_lshl_add_u64 v[2:3], s[80:81], 0, v[2:3]
	global_load_dwordx4 v[152:155], v[2:3], off
	s_cmp_lg_u32 s45, 0
	s_cbranch_scc1 .LBB0_3758
	global_load_dwordx4 v[2:5], v[180:181], off
	global_load_dwordx4 v[6:9], v[182:183], off
	global_load_dwordx4 v[10:13], v[184:185], off
	global_load_dwordx4 v[14:17], v[186:187], off
	global_load_dwordx4 v[120:123], v[188:189], off
	global_load_dwordx4 v[132:135], v[190:191], off
	v_lshl_add_u64 v[18:19], v[188:189], 0, s[12:13]
	v_lshl_add_u64 v[20:21], v[190:191], 0, s[12:13]
	global_load_dwordx4 v[124:127], v[18:19], off
	global_load_dwordx4 v[128:131], v[20:21], off
	s_waitcnt vmcnt(7)
	ds_write_b128 v199, v[2:5]
	s_waitcnt vmcnt(6)
	ds_write_b128 v199, v[6:9] offset:8192
	s_waitcnt vmcnt(5)
	ds_write_b128 v199, v[10:13] offset:16384
	s_waitcnt vmcnt(4)
	ds_write_b128 v199, v[14:17] offset:24576

.LBB0_3759:
	s_add_i32 s50, s51, 2
	s_cmp_ge_u32 s50, s48
	s_cselect_b64 s[22:23], -1, 0
	v_xor_b32_e32 v199, 0x8000, v199
	v_xor_b32_e32 v200, 0x8000, v200
	v_xor_b32_e32 v157, 0x8000, v157
	s_waitcnt lgkmcnt(0)
	s_barrier
	s_waitcnt vmcnt(0)
	ds_write_b128 v199, v[120:123]
	ds_write_b128 v199, v[132:135] offset:8192
	ds_write_b128 v199, v[124:127] offset:16384
	ds_write_b128 v199, v[128:131] offset:24576
	s_and_b64 vcc, exec, s[22:23]
	s_cbranch_vccnz .LBB0_3761
	global_load_dwordx4 v[2:5], v[196:197], off
.LBB0_3761:
	s_add_i32 s0, s51, 4
	s_sub_i32 s1, s0, s48
	s_min_u32 s2, s0, s1
	s_lshl_b64 s[0:1], s[2:3], 13
	v_lshl_add_u64 v[6:7], v[180:181], 0, s[0:1]
	v_lshl_add_u64 v[8:9], v[182:183], 0, s[0:1]
	global_load_dwordx4 v[120:123], v[6:7], off
	global_load_dwordx4 v[132:135], v[8:9], off
	s_add_i32 s0, s51, 5
	s_sub_i32 s1, s0, s48
	s_min_u32 s2, s0, s1
	s_lshl_b64 s[0:1], s[2:3], 13
	v_lshl_add_u64 v[6:7], v[180:181], 0, s[0:1]
	v_lshl_add_u64 v[8:9], v[182:183], 0, s[0:1]
	global_load_dwordx4 v[124:127], v[6:7], off
	global_load_dwordx4 v[128:131], v[8:9], off
	s_cmp_gt_u32 s51, s47
	s_cbranch_scc1 .LBB0_3765
	ds_read_b128 v[6:9], v200
	ds_read_b128 v[10:13], v200 offset:512
	v_lshrrev_b32_e32 v1, v160, v152
	v_lshrrev_b32_e32 v14, v160, v153
	v_bitop3_b32 v228, v1, s27, v1 bitop3:0xc
	v_bitop3_b32 v229, v1, s28, v1 bitop3:0xc
	v_bitop3_b32 v230, v1, s29, v1 bitop3:0xc
	v_bitop3_b32 v231, v1, s30, v1 bitop3:0xc
	s_waitcnt lgkmcnt(1)
	v_mfma_f32_32x32x16_bf16 v[80:95], v[6:9], v[144:147], v[64:79]
	v_mul_u32_u24_e32 v228, 0xf000, v228
	v_mul_u32_u24_e32 v229, 0x7800, v229
	v_mul_u32_u24_e32 v230, 0x3c00, v230
	v_mul_u32_u24_e32 v231, 0x1e00, v231
	s_waitcnt lgkmcnt(0)
	v_mfma_f32_32x32x16_bf16 v[96:111], v[10:13], v[144:147], v[64:79]
	ds_read_b128 v[6:9], v200 offset:2048
	ds_read_b128 v[10:13], v200 offset:2560
	v_bitop3_b32 v232, v14, s27, v14 bitop3:0xc
	v_bitop3_b32 v233, v14, s28, v14 bitop3:0xc
	v_bitop3_b32 v234, v14, s29, v14 bitop3:0xc
	v_bitop3_b32 v235, v14, s30, v14 bitop3:0xc
	v_mul_u32_u24_e32 v232, 0xf000, v232
	v_mul_u32_u24_e32 v233, 0x7800, v233
	v_mul_u32_u24_e32 v234, 0x3c00, v234
	v_mul_u32_u24_e32 v235, 0x1e00, v235
	s_waitcnt lgkmcnt(1)
	v_mfma_f32_32x32x16_bf16 v[80:95], v[6:9], v[136:139], v[80:95]
	v_bitop3_b32 v236, v1, s31, v1 bitop3:0xc
	v_bitop3_b32 v237, v1, s33, v1 bitop3:0xc
	v_bitop3_b32 v238, v1, s34, v1 bitop3:0xc
	v_bitop3_b32 v239, v1, s35, v1 bitop3:0xc
	s_waitcnt lgkmcnt(0)
	v_mfma_f32_32x32x16_bf16 v[96:111], v[10:13], v[136:139], v[96:111]
	ds_read_b128 v[6:9], v200 offset:4096
	ds_read_b128 v[10:13], v200 offset:4608
	v_mul_u32_u24_e32 v236, 0xf00, v236
	v_mul_u32_u24_e32 v237, 0x780, v237
	v_mul_u32_u24_e32 v238, 0x3c0, v238
	v_mul_u32_u24_e32 v239, 0x1e0, v239
	v_bitop3_b32 v224, v14, s31, v14 bitop3:0xc
	v_bitop3_b32 v225, v14, s33, v14 bitop3:0xc
	v_bitop3_b32 v226, v14, s34, v14 bitop3:0xc
	v_bitop3_b32 v227, v14, s35, v14 bitop3:0xc
	s_waitcnt lgkmcnt(1)
	v_mfma_f32_32x32x16_bf16 v[80:95], v[6:9], v[140:143], v[80:95]
	v_mul_u32_u24_e32 v224, 0xf00, v224
	v_mul_u32_u24_e32 v225, 0x780, v225
	v_mul_u32_u24_e32 v226, 0x3c0, v226
	v_mul_u32_u24_e32 v227, 0x1e0, v227
	s_waitcnt lgkmcnt(0)
	v_mfma_f32_32x32x16_bf16 v[96:111], v[10:13], v[140:143], v[96:111]
	ds_read_b128 v[6:9], v200 offset:6144
	ds_read_b128 v[10:13], v200 offset:6656
	s_xor_b64 s[4:5], s[20:21], -1
	s_waitcnt lgkmcnt(1)
	v_mfma_f32_32x32x16_bf16 v[80:95], v[6:9], v[148:151], v[80:95]
	s_waitcnt lgkmcnt(0)
	v_mfma_f32_32x32x16_bf16 v[96:111], v[10:13], v[148:151], v[96:111]
	v_mfma_f32_32x32x16_bf16 v[80:95], v[112:115], v[228:231], v[80:95]
	v_mfma_f32_32x32x16_bf16 v[96:111], v[112:115], v[232:235], v[96:111]
	v_mfma_f32_32x32x16_bf16 v[80:95], v[116:119], v[236:239], v[80:95]
	v_mfma_f32_32x32x16_bf16 v[96:111], v[116:119], v[224:227], v[96:111]
	s_nop 15
	s_nop 7
	v_max3_f32 v1, v80, v81, v82
	v_max3_f32 v6, v83, v84, v85
	v_max3_f32 v1, v1, v86, v87
	v_max3_f32 v6, v6, v88, v89
	v_max3_f32 v1, v1, v90, v91
	v_max3_f32 v6, v6, v92, v93
	v_max3_f32 v1, v1, v94, v95
	v_max_f32 v1, v1, v6
	s_nop 0
	v_max3_f32 v7, v96, v97, v98
	v_max3_f32 v6, v99, v100, v101
	v_max3_f32 v7, v7, v102, v103
	v_max3_f32 v6, v6, v104, v105
	v_max3_f32 v7, v7, v106, v107
	v_max3_f32 v6, v6, v108, v109
	v_max3_f32 v7, v7, v110, v111
	v_max3_f32 v7, v7, v6, v1
	s_nop 0
	v_mov_b32_e32 v1, v7
	s_nop 1
	v_permlane32_swap_b32_e32 v7, v1
	v_max_f32_e32 v1, v1, v1
	v_max_f32_e32 v6, v7, v7
	v_max_f32_e32 v1, v6, v1
	v_cmp_lt_f32_e64 s[0:1], s36, v1
	s_and_b64 s[10:11], s[0:1], s[4:5]
	v_cmp_lt_f32_e32 vcc, s37, v1
	s_or_b64 s[4:5], vcc, s[10:11]
	v_cndmask_b32_e64 v6, 0, 1, s[4:5]
	v_cmp_ne_u32_e32 vcc, 0, v6
	s_cbranch_vccz .LBB0_3764
	v_cndmask_b32_e64 v6, 0, v1, s[4:5]
	v_exp_f32_e64 v1, -v6
	v_add_f32_e32 v171, v171, v6
	s_or_b64 s[0:1], s[20:21], s[0:1]
	v_xor_b32_e32 v64, 0x80000000, v171
	v_cndmask_b32_e64 v8, v1, 1.0, s[10:11]
	s_andn2_b64 s[4:5], s[20:21], exec
	s_and_b64 s[0:1], s[0:1], exec
	v_pk_add_f32 v[80:81], v[80:81], v[6:7] op_sel_hi:[1,0] neg_lo:[0,1] neg_hi:[0,1]
	v_pk_add_f32 v[96:97], v[96:97], v[6:7] op_sel_hi:[1,0] neg_lo:[0,1] neg_hi:[0,1]
	v_pk_add_f32 v[82:83], v[82:83], v[6:7] op_sel_hi:[1,0] neg_lo:[0,1] neg_hi:[0,1]
	v_pk_add_f32 v[98:99], v[98:99], v[6:7] op_sel_hi:[1,0] neg_lo:[0,1] neg_hi:[0,1]
	v_pk_add_f32 v[84:85], v[84:85], v[6:7] op_sel_hi:[1,0] neg_lo:[0,1] neg_hi:[0,1]
	v_pk_add_f32 v[100:101], v[100:101], v[6:7] op_sel_hi:[1,0] neg_lo:[0,1] neg_hi:[0,1]
	v_pk_add_f32 v[86:87], v[86:87], v[6:7] op_sel_hi:[1,0] neg_lo:[0,1] neg_hi:[0,1]
	v_pk_add_f32 v[102:103], v[102:103], v[6:7] op_sel_hi:[1,0] neg_lo:[0,1] neg_hi:[0,1]
	v_pk_add_f32 v[88:89], v[88:89], v[6:7] op_sel_hi:[1,0] neg_lo:[0,1] neg_hi:[0,1]
	v_pk_add_f32 v[104:105], v[104:105], v[6:7] op_sel_hi:[1,0] neg_lo:[0,1] neg_hi:[0,1]
	v_pk_add_f32 v[90:91], v[90:91], v[6:7] op_sel_hi:[1,0] neg_lo:[0,1] neg_hi:[0,1]
	v_pk_add_f32 v[106:107], v[106:107], v[6:7] op_sel_hi:[1,0] neg_lo:[0,1] neg_hi:[0,1]
	v_pk_add_f32 v[92:93], v[92:93], v[6:7] op_sel_hi:[1,0] neg_lo:[0,1] neg_hi:[0,1]
	v_pk_add_f32 v[108:109], v[108:109], v[6:7] op_sel_hi:[1,0] neg_lo:[0,1] neg_hi:[0,1]
	v_pk_add_f32 v[94:95], v[94:95], v[6:7] op_sel_hi:[1,0] neg_lo:[0,1] neg_hi:[0,1]
	v_pk_add_f32 v[110:111], v[110:111], v[6:7] op_sel_hi:[1,0] neg_lo:[0,1] neg_hi:[0,1]
	v_mov_b32_e32 v65, v64
	v_mov_b32_e32 v66, v64
	v_mov_b32_e32 v67, v64
	v_mov_b32_e32 v68, v64
	v_mov_b32_e32 v69, v64
	v_mov_b32_e32 v70, v64
	v_mov_b32_e32 v71, v64
	v_mov_b32_e32 v72, v64
	v_mov_b32_e32 v73, v64
	v_mov_b32_e32 v74, v64
	v_mov_b32_e32 v75, v64
	v_mov_b32_e32 v76, v64
	v_mov_b32_e32 v77, v64
	v_mov_b32_e32 v78, v64
	v_mov_b32_e32 v79, v64
	v_pk_mul_f32 v[30:31], v[30:31], v[8:9] op_sel_hi:[1,0]
	v_pk_mul_f32 v[28:29], v[28:29], v[8:9] op_sel_hi:[1,0]
	v_pk_mul_f32 v[26:27], v[26:27], v[8:9] op_sel_hi:[1,0]
	v_pk_mul_f32 v[24:25], v[24:25], v[8:9] op_sel_hi:[1,0]
	v_pk_mul_f32 v[22:23], v[22:23], v[8:9] op_sel_hi:[1,0]
	v_pk_mul_f32 v[20:21], v[20:21], v[8:9] op_sel_hi:[1,0]
	v_pk_mul_f32 v[18:19], v[18:19], v[8:9] op_sel_hi:[1,0]
	v_pk_mul_f32 v[16:17], v[16:17], v[8:9] op_sel_hi:[1,0]
	v_pk_mul_f32 v[46:47], v[46:47], v[8:9] op_sel_hi:[1,0]
	v_pk_mul_f32 v[44:45], v[44:45], v[8:9] op_sel_hi:[1,0]
	v_pk_mul_f32 v[42:43], v[42:43], v[8:9] op_sel_hi:[1,0]
	v_pk_mul_f32 v[40:41], v[40:41], v[8:9] op_sel_hi:[1,0]
	v_pk_mul_f32 v[38:39], v[38:39], v[8:9] op_sel_hi:[1,0]
	v_pk_mul_f32 v[36:37], v[36:37], v[8:9] op_sel_hi:[1,0]
	v_pk_mul_f32 v[34:35], v[34:35], v[8:9] op_sel_hi:[1,0]
	v_pk_mul_f32 v[32:33], v[32:33], v[8:9] op_sel_hi:[1,0]
	v_pk_mul_f32 v[62:63], v[62:63], v[8:9] op_sel_hi:[1,0]
	v_pk_mul_f32 v[60:61], v[60:61], v[8:9] op_sel_hi:[1,0]
	v_pk_mul_f32 v[58:59], v[58:59], v[8:9] op_sel_hi:[1,0]
	v_pk_mul_f32 v[56:57], v[56:57], v[8:9] op_sel_hi:[1,0]
	v_pk_mul_f32 v[54:55], v[54:55], v[8:9] op_sel_hi:[1,0]
	v_pk_mul_f32 v[52:53], v[52:53], v[8:9] op_sel_hi:[1,0]
	v_pk_mul_f32 v[50:51], v[50:51], v[8:9] op_sel_hi:[1,0]
	v_pk_mul_f32 v[48:49], v[48:49], v[8:9] op_sel_hi:[1,0]
	s_or_b64 s[20:21], s[4:5], s[0:1]

.LBB0_3765:
	s_cmp_ge_u32 s51, s47
	s_cbranch_scc1 .LBB0_3770
	ds_read_b128 v[6:9], v200 offset:16384
	ds_read_b128 v[10:13], v200 offset:16896
	v_lshrrev_b32_e32 v1, v160, v154
	v_lshrrev_b32_e32 v14, v160, v155
	v_bitop3_b32 v228, v1, s27, v1 bitop3:0xc
	v_bitop3_b32 v229, v1, s28, v1 bitop3:0xc
	v_bitop3_b32 v230, v1, s29, v1 bitop3:0xc
	v_bitop3_b32 v231, v1, s30, v1 bitop3:0xc
	s_waitcnt lgkmcnt(1)
	v_mfma_f32_32x32x16_bf16 v[80:95], v[6:9], v[144:147], v[64:79]
	v_mul_u32_u24_e32 v228, 0xf000, v228
	v_mul_u32_u24_e32 v229, 0x7800, v229
	v_mul_u32_u24_e32 v230, 0x3c00, v230
	v_mul_u32_u24_e32 v231, 0x1e00, v231
	s_waitcnt lgkmcnt(0)
	v_mfma_f32_32x32x16_bf16 v[96:111], v[10:13], v[144:147], v[64:79]
	ds_read_b128 v[6:9], v200 offset:18432
	ds_read_b128 v[10:13], v200 offset:18944
	v_bitop3_b32 v232, v14, s27, v14 bitop3:0xc
	v_bitop3_b32 v233, v14, s28, v14 bitop3:0xc
	v_bitop3_b32 v234, v14, s29, v14 bitop3:0xc
	v_bitop3_b32 v235, v14, s30, v14 bitop3:0xc
	v_mul_u32_u24_e32 v232, 0xf000, v232
	v_mul_u32_u24_e32 v233, 0x7800, v233
	v_mul_u32_u24_e32 v234, 0x3c00, v234
	v_mul_u32_u24_e32 v235, 0x1e00, v235
	s_waitcnt lgkmcnt(1)
	v_mfma_f32_32x32x16_bf16 v[80:95], v[6:9], v[136:139], v[80:95]
	v_bitop3_b32 v236, v1, s31, v1 bitop3:0xc
	v_bitop3_b32 v237, v1, s33, v1 bitop3:0xc
	v_bitop3_b32 v238, v1, s34, v1 bitop3:0xc
	v_bitop3_b32 v239, v1, s35, v1 bitop3:0xc
	s_waitcnt lgkmcnt(0)
	v_mfma_f32_32x32x16_bf16 v[96:111], v[10:13], v[136:139], v[96:111]
	ds_read_b128 v[6:9], v200 offset:20480
	ds_read_b128 v[10:13], v200 offset:20992
	v_mul_u32_u24_e32 v236, 0xf00, v236
	v_mul_u32_u24_e32 v237, 0x780, v237
	v_mul_u32_u24_e32 v238, 0x3c0, v238
	v_mul_u32_u24_e32 v239, 0x1e0, v239
	v_bitop3_b32 v224, v14, s31, v14 bitop3:0xc
	v_bitop3_b32 v225, v14, s33, v14 bitop3:0xc
	v_bitop3_b32 v226, v14, s34, v14 bitop3:0xc
	v_bitop3_b32 v227, v14, s35, v14 bitop3:0xc
	s_waitcnt lgkmcnt(1)
	v_mfma_f32_32x32x16_bf16 v[80:95], v[6:9], v[140:143], v[80:95]
	v_mul_u32_u24_e32 v224, 0xf00, v224
	v_mul_u32_u24_e32 v225, 0x780, v225
	v_mul_u32_u24_e32 v226, 0x3c0, v226
	v_mul_u32_u24_e32 v227, 0x1e0, v227
	s_waitcnt lgkmcnt(0)
	v_mfma_f32_32x32x16_bf16 v[96:111], v[10:13], v[140:143], v[96:111]
	ds_read_b128 v[6:9], v200 offset:22528
	ds_read_b128 v[10:13], v200 offset:23040
	s_xor_b64 s[4:5], s[20:21], -1
	v_cndmask_b32_e64 v1, 0, 1, s[4:5]
	v_cmp_ne_u32_e32 vcc, 0, v1
	s_waitcnt lgkmcnt(1)
	v_mfma_f32_32x32x16_bf16 v[80:95], v[6:9], v[148:151], v[80:95]
	s_waitcnt lgkmcnt(0)
	v_mfma_f32_32x32x16_bf16 v[96:111], v[10:13], v[148:151], v[96:111]
	v_mfma_f32_32x32x16_bf16 v[80:95], v[112:115], v[228:231], v[80:95]
	v_mfma_f32_32x32x16_bf16 v[96:111], v[112:115], v[232:235], v[96:111]
	v_mfma_f32_32x32x16_bf16 v[80:95], v[116:119], v[236:239], v[80:95]
	v_mfma_f32_32x32x16_bf16 v[96:111], v[116:119], v[224:227], v[96:111]
	s_cbranch_vccz .LBB0_3769
	s_nop 15
	s_nop 7
	v_max3_f32 v1, v80, v81, v82
	v_max3_f32 v6, v83, v84, v85
	v_max3_f32 v1, v1, v86, v87
	v_max3_f32 v6, v6, v88, v89
	v_max3_f32 v1, v1, v90, v91
	v_max3_f32 v6, v6, v92, v93
	v_max3_f32 v1, v1, v94, v95
	v_max_f32 v1, v1, v6
	s_nop 0
	v_max3_f32 v7, v96, v97, v98
	v_max3_f32 v6, v99, v100, v101
	v_max3_f32 v7, v7, v102, v103
	v_max3_f32 v6, v6, v104, v105
	v_max3_f32 v7, v7, v106, v107
	v_max3_f32 v6, v6, v108, v109
	v_max3_f32 v7, v7, v110, v111
	v_max3_f32 v7, v7, v6, v1
	s_nop 0
	v_mov_b32_e32 v1, v7
	s_nop 1
	v_permlane32_swap_b32_e32 v7, v1
	v_max_f32_e32 v1, v1, v1
	v_max_f32_e32 v6, v7, v7
	v_max_f32_e32 v1, v6, v1
	v_cmp_lt_f32_e64 s[0:1], s36, v1
	s_and_b64 s[10:11], s[0:1], s[4:5]
	v_cmp_lt_f32_e32 vcc, s37, v1
	s_or_b64 s[4:5], vcc, s[10:11]
	v_cndmask_b32_e64 v6, 0, 1, s[4:5]
	v_cmp_ne_u32_e32 vcc, 0, v6
	s_cbranch_vccz .LBB0_3769
	v_cndmask_b32_e64 v1, 0, v1, s[4:5]
	v_exp_f32_e64 v6, -v1
	v_add_f32_e32 v171, v171, v1
	s_or_b64 s[0:1], s[20:21], s[0:1]
	v_xor_b32_e32 v64, 0x80000000, v171
	v_cndmask_b32_e64 v6, v6, 1.0, s[10:11]
	s_andn2_b64 s[4:5], s[20:21], exec
	s_and_b64 s[0:1], s[0:1], exec
	v_mov_b32_e32 v65, v64
	v_mov_b32_e32 v66, v64
	v_mov_b32_e32 v67, v64
	v_mov_b32_e32 v68, v64
	v_mov_b32_e32 v69, v64
	v_mov_b32_e32 v70, v64
	v_mov_b32_e32 v71, v64
	v_mov_b32_e32 v72, v64
	v_mov_b32_e32 v73, v64
	v_mov_b32_e32 v74, v64
	v_mov_b32_e32 v75, v64
	v_mov_b32_e32 v76, v64
	v_mov_b32_e32 v77, v64
	v_mov_b32_e32 v78, v64
	v_mov_b32_e32 v79, v64
	v_pk_mul_f32 v[30:31], v[30:31], v[6:7] op_sel_hi:[1,0]
	v_pk_mul_f32 v[28:29], v[28:29], v[6:7] op_sel_hi:[1,0]
	v_pk_mul_f32 v[26:27], v[26:27], v[6:7] op_sel_hi:[1,0]
	v_pk_mul_f32 v[24:25], v[24:25], v[6:7] op_sel_hi:[1,0]
	v_pk_mul_f32 v[22:23], v[22:23], v[6:7] op_sel_hi:[1,0]
	v_pk_mul_f32 v[20:21], v[20:21], v[6:7] op_sel_hi:[1,0]
	v_pk_mul_f32 v[18:19], v[18:19], v[6:7] op_sel_hi:[1,0]
	v_pk_mul_f32 v[16:17], v[16:17], v[6:7] op_sel_hi:[1,0]
	v_pk_mul_f32 v[46:47], v[46:47], v[6:7] op_sel_hi:[1,0]
	v_pk_mul_f32 v[44:45], v[44:45], v[6:7] op_sel_hi:[1,0]
	v_pk_mul_f32 v[42:43], v[42:43], v[6:7] op_sel_hi:[1,0]
	v_pk_mul_f32 v[40:41], v[40:41], v[6:7] op_sel_hi:[1,0]
	v_pk_mul_f32 v[38:39], v[38:39], v[6:7] op_sel_hi:[1,0]
	v_pk_mul_f32 v[36:37], v[36:37], v[6:7] op_sel_hi:[1,0]
	v_pk_mul_f32 v[34:35], v[34:35], v[6:7] op_sel_hi:[1,0]
	v_pk_mul_f32 v[32:33], v[32:33], v[6:7] op_sel_hi:[1,0]
	v_pk_mul_f32 v[62:63], v[62:63], v[6:7] op_sel_hi:[1,0]
	v_pk_mul_f32 v[60:61], v[60:61], v[6:7] op_sel_hi:[1,0]
	v_pk_mul_f32 v[58:59], v[58:59], v[6:7] op_sel_hi:[1,0]
	v_pk_mul_f32 v[56:57], v[56:57], v[6:7] op_sel_hi:[1,0]
	v_pk_mul_f32 v[54:55], v[54:55], v[6:7] op_sel_hi:[1,0]
	v_pk_mul_f32 v[52:53], v[52:53], v[6:7] op_sel_hi:[1,0]
	v_pk_mul_f32 v[50:51], v[50:51], v[6:7] op_sel_hi:[1,0]
	v_pk_mul_f32 v[48:49], v[48:49], v[6:7] op_sel_hi:[1,0]
	v_sub_f32_e32 v95, v95, v1
	v_sub_f32_e32 v94, v94, v1
	v_sub_f32_e32 v93, v93, v1
	v_sub_f32_e32 v92, v92, v1
	v_sub_f32_e32 v91, v91, v1
	v_sub_f32_e32 v90, v90, v1
	v_sub_f32_e32 v89, v89, v1
	v_sub_f32_e32 v88, v88, v1
	v_sub_f32_e32 v87, v87, v1
	v_sub_f32_e32 v86, v86, v1
	v_sub_f32_e32 v85, v85, v1
	v_sub_f32_e32 v84, v84, v1
	v_sub_f32_e32 v83, v83, v1
	v_sub_f32_e32 v82, v82, v1
	v_sub_f32_e32 v81, v81, v1
	v_sub_f32_e32 v80, v80, v1
	v_sub_f32_e32 v111, v111, v1
	v_sub_f32_e32 v110, v110, v1
	v_sub_f32_e32 v109, v109, v1
	v_sub_f32_e32 v108, v108, v1
	v_sub_f32_e32 v107, v107, v1
	v_sub_f32_e32 v106, v106, v1
	v_sub_f32_e32 v105, v105, v1
	v_sub_f32_e32 v104, v104, v1
	v_sub_f32_e32 v103, v103, v1
	v_sub_f32_e32 v102, v102, v1
	v_sub_f32_e32 v101, v101, v1
	v_sub_f32_e32 v100, v100, v1
	v_sub_f32_e32 v99, v99, v1
	v_sub_f32_e32 v98, v98, v1
	v_sub_f32_e32 v97, v97, v1
	v_sub_f32_e32 v96, v96, v1
	s_or_b64 s[20:21], s[4:5], s[0:1]
